# v67 + attention loops: next-tile LDS stores issued inside the PV MFMA block (behind the lgkmcnt(2) wait) instead of after it
# speedup vs baseline: 1.0002x; 1.0002x over previous
.LBB0_559:
	v_sub_f32_e32 v167, v167, v227
	v_sub_f32_e32 v166, v166, v227
	v_sub_f32_e32 v165, v165, v227
	v_sub_f32_e32 v164, v164, v227
	v_exp_f32_e32 v230, v164
	v_exp_f32_e32 v231, v165
	v_exp_f32_e32 v232, v166
	v_exp_f32_e32 v233, v167
	v_sub_f32_e32 v164, v187, v227
	v_sub_f32_e32 v165, v186, v227
	v_sub_f32_e32 v166, v185, v227
	v_sub_f32_e32 v167, v184, v227
	v_exp_f32_e32 v234, v167
	v_exp_f32_e32 v235, v166
	v_exp_f32_e32 v236, v165
	v_exp_f32_e32 v237, v164
	v_sub_f32_e32 v164, v195, v227
	v_sub_f32_e32 v165, v194, v227
	v_sub_f32_e32 v166, v193, v227
	v_sub_f32_e32 v167, v192, v227
	v_sub_f32_e32 v171, v171, v221
	v_sub_f32_e32 v170, v170, v221
	v_sub_f32_e32 v169, v169, v221
	v_sub_f32_e32 v168, v168, v221
	v_sub_f32_e32 v175, v175, v221
	v_sub_f32_e32 v174, v174, v221
	v_sub_f32_e32 v173, v173, v221
	v_sub_f32_e32 v172, v172, v221
	v_sub_f32_e32 v183, v183, v221
	v_sub_f32_e32 v182, v182, v221
	v_sub_f32_e32 v181, v181, v221
	v_sub_f32_e32 v180, v180, v221
	v_sub_f32_e32 v179, v179, v221
	v_sub_f32_e32 v178, v178, v221
	v_sub_f32_e32 v177, v177, v221
	v_sub_f32_e32 v176, v176, v221
	v_exp_f32_e32 v192, v167
	v_exp_f32_e32 v193, v166
	v_exp_f32_e32 v194, v165
	v_exp_f32_e32 v195, v164
	v_sub_f32_e32 v164, v191, v227
	v_sub_f32_e32 v165, v190, v227
	v_sub_f32_e32 v166, v189, v227
	v_sub_f32_e32 v167, v188, v227
	v_exp_f32_e32 v168, v168
	v_exp_f32_e32 v169, v169
	v_exp_f32_e32 v170, v170
	v_exp_f32_e32 v171, v171
	v_exp_f32_e32 v172, v172
	v_exp_f32_e32 v173, v173
	v_exp_f32_e32 v174, v174
	v_exp_f32_e32 v175, v175
	v_exp_f32_e32 v180, v180
	v_exp_f32_e32 v181, v181
	v_exp_f32_e32 v182, v182
	v_exp_f32_e32 v183, v183
	v_exp_f32_e32 v176, v176
	v_exp_f32_e32 v177, v177
	v_exp_f32_e32 v178, v178
	v_exp_f32_e32 v179, v179
	v_exp_f32_e32 v190, v167
	v_exp_f32_e32 v191, v166
	v_exp_f32_e32 v238, v165
	v_exp_f32_e32 v239, v164
	v_pk_add_f32 v[188:189], v[168:169], v[172:173]
	v_pk_add_f32 v[240:241], v[170:171], v[174:175]
	v_pk_add_f32 v[242:243], v[180:181], v[176:177]
	v_pk_add_f32 v[244:245], v[182:183], v[178:179]
	v_cvt_pk_bf16_f32 v184, v230, v231
	v_cvt_pk_bf16_f32 v185, v232, v233
	v_cvt_pk_bf16_f32 v164, v192, v193
	v_cvt_pk_bf16_f32 v166, v190, v191
	v_pk_add_f32 v[240:241], v[240:241], v[244:245]
	v_pk_add_f32 v[188:189], v[188:189], v[242:243]
	v_pk_add_f32 v[230:231], v[230:231], v[234:235]
	v_pk_add_f32 v[232:233], v[232:233], v[236:237]
	v_pk_add_f32 v[190:191], v[192:193], v[190:191]
	v_pk_add_f32 v[192:193], v[194:195], v[238:239]
	v_add_f32_e32 v188, v188, v189
	v_add_f32_e32 v189, v240, v241
	v_pk_add_f32 v[192:193], v[232:233], v[192:193]
	v_pk_add_f32 v[190:191], v[230:231], v[190:191]
	v_add_f32_e32 v188, v188, v189
	v_add_f32_e32 v189, v190, v191
	v_add_f32_e32 v190, v192, v193
	v_cvt_pk_bf16_f32 v186, v234, v235
	v_cvt_pk_bf16_f32 v187, v236, v237
	v_add_f32_e32 v189, v189, v190
	v_cvt_pk_bf16_f32 v190, v168, v169
	v_cvt_pk_bf16_f32 v191, v170, v171
	v_cvt_pk_bf16_f32 v192, v172, v173
	v_cvt_pk_bf16_f32 v193, v174, v175
	s_waitcnt lgkmcnt(14)
	v_mfma_f32_16x16x32_bf16 v[4:7], v[156:159], v[184:187], v[4:7]
	v_cvt_pk_bf16_f32 v165, v194, v195
	v_cvt_pk_bf16_f32 v167, v238, v239
	v_cvt_pk_bf16_f32 v168, v180, v181
	v_mfma_f32_16x16x32_bf16 v[64:67], v[156:159], v[190:193], v[64:67]
	v_cvt_pk_bf16_f32 v169, v182, v183
	v_cvt_pk_bf16_f32 v170, v176, v177
	v_cvt_pk_bf16_f32 v171, v178, v179
	v_mfma_f32_16x16x32_bf16 v[8:11], v[160:163], v[184:187], v[8:11]
	s_and_b32 s1, s0, 0x8000
	s_add_i32 s1, s1, 0
	s_add_i32 s8, s8, 64
	v_mfma_f32_16x16x32_bf16 v[60:63], v[160:163], v[190:193], v[60:63]
	s_add_i32 s0, s0, 0x8000
	s_mov_b64 s[10:11], 0x10000
	s_add_i32 s7, s7, 1
	v_mfma_f32_16x16x32_bf16 v[12:15], v[152:155], v[184:187], v[12:15]
	v_fmac_f32_e32 v188, v229, v204
	v_fmac_f32_e32 v189, v228, v2
	v_lshl_add_u64 v[202:203], v[202:203], 0, s[10:11]
	v_mfma_f32_16x16x32_bf16 v[56:59], v[152:155], v[190:193], v[56:59]
	s_cmp_eq_u32 s8, 64
	v_add_u32_e32 v2, s1, v220
	v_mfma_f32_16x16x32_bf16 v[16:19], v[148:151], v[184:187], v[16:19]
	v_mfma_f32_16x16x32_bf16 v[52:55], v[148:151], v[190:193], v[52:55]
	v_mfma_f32_16x16x32_bf16 v[20:23], v[144:147], v[184:187], v[20:23]
	v_mfma_f32_16x16x32_bf16 v[48:51], v[144:147], v[190:193], v[48:51]
	s_waitcnt lgkmcnt(10)
	v_mfma_f32_16x16x32_bf16 v[24:27], v[140:143], v[184:187], v[24:27]
	v_mfma_f32_16x16x32_bf16 v[44:47], v[140:143], v[190:193], v[44:47]
	s_waitcnt lgkmcnt(6)
	v_mfma_f32_16x16x32_bf16 v[28:31], v[136:139], v[184:187], v[28:31]
	v_mfma_f32_16x16x32_bf16 v[40:43], v[136:139], v[190:193], v[40:43]
	s_waitcnt lgkmcnt(2)
	v_mfma_f32_16x16x32_bf16 v[32:35], v[132:135], v[184:187], v[32:35]
	v_mfma_f32_16x16x32_bf16 v[36:39], v[132:135], v[190:193], v[36:39]
	v_add_u32_e32 v250, s1, v219
	s_waitcnt vmcnt(0)
	ds_write_b128 v250, v[84:87]
	ds_write_b128 v250, v[88:91] offset:8192
	ds_write_b128 v2, v[92:95] offset:16384
	ds_write_b128 v2, v[96:99] offset:24576
	v_mfma_f32_16x16x32_bf16 v[4:7], v[112:115], v[164:167], v[4:7]
	v_mfma_f32_16x16x32_bf16 v[64:67], v[112:115], v[168:171], v[64:67]
	v_mfma_f32_16x16x32_bf16 v[8:11], v[116:119], v[164:167], v[8:11]
	v_mfma_f32_16x16x32_bf16 v[60:63], v[116:119], v[168:171], v[60:63]
	v_mfma_f32_16x16x32_bf16 v[12:15], v[124:127], v[164:167], v[12:15]
	v_mfma_f32_16x16x32_bf16 v[56:59], v[124:127], v[168:171], v[56:59]
	v_mfma_f32_16x16x32_bf16 v[16:19], v[128:131], v[164:167], v[16:19]
	v_mfma_f32_16x16x32_bf16 v[52:55], v[128:131], v[168:171], v[52:55]
	v_mfma_f32_16x16x32_bf16 v[20:23], v[120:123], v[164:167], v[20:23]
	v_mfma_f32_16x16x32_bf16 v[48:51], v[120:123], v[168:171], v[48:51]
	v_mfma_f32_16x16x32_bf16 v[24:27], v[108:111], v[164:167], v[24:27]
	v_mfma_f32_16x16x32_bf16 v[44:47], v[108:111], v[168:171], v[44:47]
	v_mfma_f32_16x16x32_bf16 v[28:31], v[104:107], v[164:167], v[28:31]
	v_mfma_f32_16x16x32_bf16 v[40:43], v[104:107], v[168:171], v[40:43]
	s_waitcnt lgkmcnt(0)
	v_mfma_f32_16x16x32_bf16 v[32:35], v[100:103], v[164:167], v[32:35]
	v_mfma_f32_16x16x32_bf16 v[36:39], v[100:103], v[168:171], v[36:39]
	s_waitcnt lgkmcnt(0)
	s_barrier
	s_cbranch_scc1 .LBB0_561
	v_mov_b32_e32 v228, v189
	v_mov_b32_e32 v230, v227
	v_mov_b32_e32 v229, v188
	v_mov_b32_e32 v204, v221
	s_branch .LBB0_553

.LBB0_572:
	v_sub_f32_e32 v167, v167, v231
	v_sub_f32_e32 v166, v166, v231
	v_sub_f32_e32 v165, v165, v231
	v_sub_f32_e32 v164, v164, v231
	v_exp_f32_e32 v234, v164
	v_exp_f32_e32 v235, v165
	v_exp_f32_e32 v236, v166
	v_exp_f32_e32 v237, v167
	v_sub_f32_e32 v164, v171, v231
	v_sub_f32_e32 v165, v170, v231
	v_sub_f32_e32 v166, v169, v231
	v_sub_f32_e32 v167, v168, v231
	v_exp_f32_e32 v238, v167
	v_exp_f32_e32 v239, v166
	v_exp_f32_e32 v240, v165
	v_exp_f32_e32 v241, v164
	v_sub_f32_e32 v164, v191, v231
	v_sub_f32_e32 v165, v190, v231
	v_sub_f32_e32 v166, v189, v231
	v_sub_f32_e32 v167, v188, v231
	v_exp_f32_e32 v190, v167
	v_exp_f32_e32 v191, v166
	v_exp_f32_e32 v242, v165
	v_exp_f32_e32 v243, v164
	v_sub_f32_e32 v164, v195, v231
	v_sub_f32_e32 v165, v194, v231
	v_sub_f32_e32 v166, v193, v231
	v_sub_f32_e32 v167, v192, v231
	v_exp_f32_e32 v192, v167
	v_exp_f32_e32 v193, v166
	v_exp_f32_e32 v194, v165
	v_exp_f32_e32 v195, v164
	v_sub_f32_e32 v175, v175, v230
	v_sub_f32_e32 v174, v174, v230
	v_sub_f32_e32 v173, v173, v230
	v_sub_f32_e32 v172, v172, v230
	v_sub_f32_e32 v179, v179, v230
	v_sub_f32_e32 v178, v178, v230
	v_sub_f32_e32 v177, v177, v230
	v_sub_f32_e32 v176, v176, v230
	v_sub_f32_e32 v183, v183, v230
	v_sub_f32_e32 v182, v182, v230
	v_sub_f32_e32 v181, v181, v230
	v_sub_f32_e32 v180, v180, v230
	v_sub_f32_e32 v187, v187, v230
	v_sub_f32_e32 v186, v186, v230
	v_sub_f32_e32 v185, v185, v230
	v_sub_f32_e32 v184, v184, v230
	v_exp_f32_e32 v172, v172
	v_exp_f32_e32 v173, v173
	v_exp_f32_e32 v174, v174
	v_exp_f32_e32 v175, v175
	v_exp_f32_e32 v176, v176
	v_exp_f32_e32 v177, v177
	v_exp_f32_e32 v178, v178
	v_exp_f32_e32 v179, v179
	v_exp_f32_e32 v180, v180
	v_exp_f32_e32 v181, v181
	v_exp_f32_e32 v182, v182
	v_exp_f32_e32 v183, v183
	v_exp_f32_e32 v184, v184
	v_exp_f32_e32 v185, v185
	v_exp_f32_e32 v186, v186
	v_exp_f32_e32 v187, v187
	v_cvt_pk_bf16_f32 v168, v234, v235
	v_cvt_pk_bf16_f32 v169, v236, v237
	v_cvt_pk_bf16_f32 v164, v190, v191
	v_cvt_pk_bf16_f32 v166, v192, v193
	v_pk_add_f32 v[234:235], v[234:235], v[238:239]
	v_pk_add_f32 v[236:237], v[236:237], v[240:241]
	v_pk_add_f32 v[190:191], v[190:191], v[192:193]
	v_pk_add_f32 v[192:193], v[242:243], v[194:195]
	v_pk_add_f32 v[188:189], v[172:173], v[176:177]
	v_pk_add_f32 v[244:245], v[174:175], v[178:179]
	v_pk_add_f32 v[246:247], v[180:181], v[184:185]
	v_pk_add_f32 v[248:249], v[182:183], v[186:187]
	v_pk_add_f32 v[192:193], v[236:237], v[192:193]
	v_pk_add_f32 v[190:191], v[234:235], v[190:191]
	v_cvt_pk_bf16_f32 v167, v194, v195
	v_pk_add_f32 v[244:245], v[244:245], v[248:249]
	v_pk_add_f32 v[188:189], v[188:189], v[246:247]
	v_pk_mov_b32 v[194:195], v[190:191], v[192:193] op_sel:[1,0]
	v_mov_b32_e32 v191, v193
	v_add_f32_e32 v188, v188, v189
	v_add_f32_e32 v189, v244, v245
	v_pk_add_f32 v[190:191], v[194:195], v[190:191]
	v_cvt_pk_bf16_f32 v170, v238, v239
	v_cvt_pk_bf16_f32 v171, v240, v241
	v_add_f32_e32 v188, v188, v189
	v_add_f32_e32 v189, v190, v191
	v_cvt_pk_bf16_f32 v190, v172, v173
	v_cvt_pk_bf16_f32 v191, v174, v175
	v_cvt_pk_bf16_f32 v192, v176, v177
	v_cvt_pk_bf16_f32 v193, v178, v179
	s_waitcnt lgkmcnt(14)
	v_mfma_f32_16x16x32_bf16 v[4:7], v[160:163], v[168:171], v[4:7]
	v_cvt_pk_bf16_f32 v165, v242, v243
	v_cvt_pk_bf16_f32 v172, v180, v181
	v_cvt_pk_bf16_f32 v173, v182, v183
	v_mfma_f32_16x16x32_bf16 v[80:83], v[160:163], v[190:193], v[80:83]
	v_cvt_pk_bf16_f32 v174, v184, v185
	v_cvt_pk_bf16_f32 v175, v186, v187
	s_and_b32 s6, s4, 0x8000
	v_mfma_f32_16x16x32_bf16 v[8:11], v[156:159], v[168:171], v[8:11]
	s_add_i32 s6, s6, 0
	s_add_u32 s0, s0, 0x10000
	s_addc_u32 s1, s1, 0
	v_mfma_f32_16x16x32_bf16 v[76:79], v[156:159], v[190:193], v[76:79]
	s_add_i32 s4, s4, 0x8000
	v_fmac_f32_e32 v188, v233, v208
	v_fmac_f32_e32 v189, v232, v2
	v_mfma_f32_16x16x32_bf16 v[12:15], v[152:155], v[168:171], v[12:15]
	s_cmp_eq_u32 s5, s0
	v_add_u32_e32 v2, s6, v229
	v_mfma_f32_16x16x32_bf16 v[72:75], v[152:155], v[190:193], v[72:75]
	v_mfma_f32_16x16x32_bf16 v[16:19], v[148:151], v[168:171], v[16:19]
	v_mfma_f32_16x16x32_bf16 v[68:71], v[148:151], v[190:193], v[68:71]
	v_mfma_f32_16x16x32_bf16 v[20:23], v[144:147], v[168:171], v[20:23]
	v_mfma_f32_16x16x32_bf16 v[64:67], v[144:147], v[190:193], v[64:67]
	s_waitcnt lgkmcnt(10)
	v_mfma_f32_16x16x32_bf16 v[24:27], v[140:143], v[168:171], v[24:27]
	v_mfma_f32_16x16x32_bf16 v[60:63], v[140:143], v[190:193], v[60:63]
	s_waitcnt lgkmcnt(6)
	v_mfma_f32_16x16x32_bf16 v[28:31], v[136:139], v[168:171], v[28:31]
	v_mfma_f32_16x16x32_bf16 v[52:55], v[136:139], v[190:193], v[52:55]
	s_waitcnt lgkmcnt(2)
	v_mfma_f32_16x16x32_bf16 v[32:35], v[132:135], v[168:171], v[32:35]
	v_mfma_f32_16x16x32_bf16 v[56:59], v[132:135], v[190:193], v[56:59]
	v_add_u32_e32 v250, s6, v228
	s_waitcnt vmcnt(0)
	ds_write_b128 v250, v[84:87]
	ds_write_b128 v250, v[88:91] offset:8192
	ds_write_b128 v2, v[92:95] offset:16384
	ds_write_b128 v2, v[96:99] offset:24576
	v_mfma_f32_16x16x32_bf16 v[4:7], v[116:119], v[164:167], v[4:7]
	v_mfma_f32_16x16x32_bf16 v[80:83], v[116:119], v[172:175], v[80:83]
	v_mfma_f32_16x16x32_bf16 v[8:11], v[120:123], v[164:167], v[8:11]
	v_mfma_f32_16x16x32_bf16 v[76:79], v[120:123], v[172:175], v[76:79]
	v_mfma_f32_16x16x32_bf16 v[12:15], v[124:127], v[164:167], v[12:15]
	v_mfma_f32_16x16x32_bf16 v[72:75], v[124:127], v[172:175], v[72:75]
	v_mfma_f32_16x16x32_bf16 v[16:19], v[128:131], v[164:167], v[16:19]
	v_mfma_f32_16x16x32_bf16 v[68:71], v[128:131], v[172:175], v[68:71]
	v_mfma_f32_16x16x32_bf16 v[20:23], v[112:115], v[164:167], v[20:23]
	v_mfma_f32_16x16x32_bf16 v[64:67], v[112:115], v[172:175], v[64:67]
	v_mfma_f32_16x16x32_bf16 v[24:27], v[108:111], v[164:167], v[24:27]
	v_mfma_f32_16x16x32_bf16 v[60:63], v[108:111], v[172:175], v[60:63]
	v_mfma_f32_16x16x32_bf16 v[28:31], v[104:107], v[164:167], v[28:31]
	v_mfma_f32_16x16x32_bf16 v[52:55], v[104:107], v[172:175], v[52:55]
	s_waitcnt lgkmcnt(0)
	v_mfma_f32_16x16x32_bf16 v[32:35], v[100:103], v[164:167], v[32:35]
	v_mfma_f32_16x16x32_bf16 v[56:59], v[100:103], v[172:175], v[56:59]
	s_waitcnt lgkmcnt(0)
	s_barrier
	s_cbranch_scc1 .LBB0_574
	v_mov_b32_e32 v232, v189
	v_mov_b32_e32 v233, v188
	v_mov_b32_e32 v208, v230
	s_branch .LBB0_568
